# 7.4 static s_setprio 1 for attention waves 4-7 (reset at the M2 join), on v51
# speedup vs baseline: 1.0022x; 1.0022x over previous
.LBB0_1030:
	s_andn2_b64 vcc, exec, s[40:41]
	s_cbranch_vccnz .LBB0_1195
	v_readlane_b32 s54, v254, 0
	s_waitcnt vmcnt(6)
	v_mov_b32_e32 v119, v155
	s_ashr_i32 s8, s54, 3
	v_readfirstlane_b32 s6, v119
	s_ashr_i32 s9, s6, 6
	s_cmp_lt_i32 s8, 32
	s_cselect_b64 s[20:21], -1, 0
	v_cndmask_b32_e64 v0, 0, 1, s[20:21]
	v_and_b32_e32 v123, 63, v119
	s_mov_b64 s[40:41], -1
	s_and_b64 vcc, exec, s[38:39]
	v_cmp_ne_u32_e64 s[38:39], 1, v0
	s_cbranch_vccnz .LBB0_1080
	s_and_b64 vcc, exec, s[38:39]
	s_cbranch_vccnz .LBB0_1079
	s_cmp_ge_u32 s9, 4
	s_cbranch_scc0 .Lattn_prio_done
	s_setprio 1
.Lattn_prio_done:
	s_lshr_b32 s55, s54, 3
	s_add_u32 s20, s2, 0x12800000
	s_addc_u32 s21, s3, 0
	s_lshl_b32 s7, s54, 11
	v_and_b32_e32 v48, 48, v123
	s_and_b32 s24, s7, 0x3800
	s_ashr_i32 s57, s6, 7
	v_lshl_add_u64 v[0:1], s[2:3], 0, v[48:49]
	s_mov_b64 s[6:7], 0xf000000
	s_mov_b32 s18, 0x2aaaaaab
	v_lshl_add_u64 v[108:109], v[0:1], 0, s[6:7]
	v_mul_hi_i32 v0, v119, s18
	v_lshrrev_b32_e32 v1, 31, v0
	v_ashrrev_i32_e32 v0, 1, v0
	v_add_u32_e32 v0, v0, v1
	v_mul_lo_u32 v1, v0, 12
	s_waitcnt vmcnt(4)
	v_sub_u32_e32 v13, v119, v1
	v_add_u32_e32 v1, 0x200, v119
	v_mul_hi_i32 v2, v1, s18
	v_lshrrev_b32_e32 v3, 31, v2
	v_ashrrev_i32_e32 v2, 1, v2
	v_add_u32_e32 v2, v2, v3
	v_mul_lo_u32 v3, v2, 12
	v_sub_u32_e32 v14, v1, v3
	v_ashrrev_i32_e32 v1, 31, v0
	s_lshl_b32 s56, s9, 5
	v_lshl_add_u64 v[6:7], s[24:25], 0, v[0:1]
	s_add_u32 s6, s2, 0x10800000
	v_lshlrev_b64 v[8:9], 6, v[6:7]
	s_addc_u32 s7, s3, 0
	v_lshl_add_u64 v[8:9], s[20:21], 0, v[8:9]
	v_lshlrev_b32_e32 v10, 3, v13
	v_mov_b32_e32 v11, v49
	v_lshlrev_b64 v[6:7], 11, v[6:7]
	v_lshl_add_u64 v[8:9], v[10:11], 1, v[8:9]
	s_movk_i32 s26, 0xff80
	v_lshl_add_u64 v[6:7], s[6:7], 0, v[6:7]
	v_ashrrev_i32_e32 v11, 31, v10
	v_ashrrev_i32_e32 v3, 31, v2
	s_mov_b32 s27, -1
	v_lshl_add_u64 v[112:113], v[10:11], 1, v[6:7]
	v_lshl_add_u64 v[6:7], v[2:3], 0, s[24:25]
	v_lshl_add_u64 v[110:111], v[8:9], 0, s[26:27]
	v_lshlrev_b64 v[8:9], 6, v[6:7]
	v_ashrrev_i32_e32 v4, 3, v119
	v_lshl_add_u64 v[8:9], s[20:21], 0, v[8:9]
	v_lshlrev_b32_e32 v10, 3, v14
	v_mov_b32_e32 v11, v49
	v_lshlrev_b64 v[6:7], 11, v[6:7]
	v_lshl_add_u64 v[8:9], v[10:11], 1, v[8:9]
	v_lshl_add_u64 v[6:7], s[6:7], 0, v[6:7]
	v_ashrrev_i32_e32 v11, 31, v10
	v_ashrrev_i32_e32 v5, 31, v4
	v_lshl_add_u64 v[116:117], v[10:11], 1, v[6:7]
	v_lshl_add_u64 v[6:7], s[24:25], 0, v[4:5]
	v_lshlrev_b64 v[6:7], 11, v[6:7]
	v_lshl_add_u64 v[6:7], s[6:7], 0, v[6:7]
	s_movk_i32 s6, 0xd0
	v_cmp_gt_i32_e64 s[42:43], 8, v13
	v_lshlrev_b32_e32 v1, 3, v119
	v_mul_lo_u32 v0, v0, s6
	v_cndmask_b32_e64 v118, 11, 16, s[42:43]
	v_and_b32_e32 v3, 56, v1
	s_waitcnt vmcnt(3)
	v_lshl_add_u32 v125, v13, 4, v0
	v_mul_lo_u32 v2, v2, s6
	v_lshlrev_b64 v[0:1], v118, 1
	v_lshl_add_u32 v184, v14, 4, v2
	v_lshrrev_b32_e32 v1, 2, v123
	v_bfe_u32 v2, v119, 2, 2
	s_movk_i32 s6, 0x50
	v_and_or_b32 v1, v1, 12, v2
	v_lshlrev_b32_e32 v2, 3, v123
	v_mul_lo_u32 v185, v4, s6
	v_and_b32_e32 v187, 24, v2
	v_and_b32_e32 v2, 64, v205
	v_readlane_b32 s6, v255, 35
	v_mul_u32_u24_e32 v189, 0xa0, v1
	v_xor_b32_e32 v1, 16, v205
	v_add_u32_e32 v2, 64, v2
	v_readlane_b32 s7, v255, 36
	v_cmp_lt_i32_e32 vcc, v1, v2
	v_readlane_b32 s20, v255, 23
	v_lshl_add_u64 v[120:121], s[6:7], 0, v[48:49]
	s_and_b32 s6, s54, 7
	v_cndmask_b32_e32 v1, v205, v1, vcc
	s_lshl_b32 s6, s6, 22
	v_lshlrev_b32_e32 v190, 2, v1
	v_cmp_gt_i32_e64 s[44:45], 8, v14
	v_mov_b32_e32 v1, 0x800
	v_mov_b32_e32 v2, 0x10000
	v_readlane_b32 s21, v255, 24
	s_add_u32 s6, s20, s6
	v_cndmask_b32_e64 v122, v1, v2, s[44:45]
	v_lshlrev_b32_e32 v126, 1, v3
	s_addc_u32 s7, s21, 0
	v_lshlrev_b64 v[2:3], 11, v[4:5]
	v_and_b32_e32 v1, 7, v119
	v_lshl_add_u64 v[2:3], s[6:7], 0, v[2:3]
	v_lshlrev_b32_e32 v48, 4, v1
	v_readlane_b32 s6, v255, 6
	v_and_b32_e32 v12, 15, v119
	s_movk_i32 s18, 0x100
	v_mov_b32_e32 v127, v49
	v_lshl_add_u64 v[2:3], v[2:3], 0, v[48:49]
	v_readlane_b32 s7, v255, 7
	v_or_b32_e32 v106, s24, v12
	v_mov_b32_e32 v107, v49
	v_cmp_gt_i32_e64 s[40:41], s18, v119
	v_lshl_add_u64 v[114:115], v[8:9], 0, s[26:27]
	v_and_b32_e32 v186, 48, v119
	v_mul_u32_u24_e32 v188, 0xd0, v12
	v_cndmask_b32_e64 v124, 11, 16, s[44:45]
	s_waitcnt vmcnt(2)
	v_lshl_add_u64 v[128:129], v[6:7], 0, v[126:127]
	s_waitcnt vmcnt(1)
	v_lshl_add_u64 v[130:131], s[6:7], 0, v[2:3]
	v_lshlrev_b32_e32 v48, 1, v0
	s_mov_b32 s58, s8
	s_branch .LBB0_1036

.LBB0_1119:
	s_setprio 0
	v_readlane_b32 s6, v255, 22
	s_add_i32 s8, s6, 6
	v_readlane_b32 s6, v254, 1
	v_readlane_b32 s7, v254, 2
	s_cmp_ge_i32 s8, s7
	s_cbranch_scc1 .LBB0_1132
	v_readlane_b32 s6, v254, 5
	v_readlane_b32 s7, v254, 6
	s_mov_b64 s[38:39], -1
	s_and_b64 vcc, exec, s[6:7]
	s_cbranch_vccz .LBB0_1175
	s_waitcnt vmcnt(0)
	s_barrier
	s_mov_b64 s[54:55], exec
	v_readlane_b32 s6, v254, 3
	v_readlane_b32 s7, v254, 4
	s_and_b64 s[6:7], s[54:55], s[6:7]
	s_mov_b64 exec, s[6:7]
	s_cbranch_execz .LBB0_1174
	s_add_i32 s9, 0, 0x21000
	v_mov_b32_e32 v0, s9
	s_waitcnt vmcnt(0) expcnt(0) lgkmcnt(0)
	ds_read_b32 v1, v0
	v_readlane_b32 s6, v255, 14
	s_waitcnt lgkmcnt(0)
	v_cmp_ne_u32_e32 vcc, 0, v1
	v_mov_b32_e32 v0, s6
	ds_read_b32 v0, v0
	s_cbranch_vccnz .LBB0_1138
	s_mov_b32 s6, 1
	s_branch .LBB0_1125
